# v68 + P1 epilogue: write-through conv-halo (TU) store deferred past the epilogue's counted waits
# baseline (speedup 1.0000x reference)
.LBB0_146:
	v_lshl_or_b32 v170, s83, 6, v176
	v_ashrrev_i32_e32 v171, 31, v170
	v_lshlrev_b64 v[172:173], 2, v[170:171]
	v_lshl_add_u64 v[96:97], s[42:43], 0, v[172:173]
	v_lshl_add_u64 v[100:101], s[70:71], 0, v[172:173]
	v_lshl_add_u64 v[112:113], s[72:73], 0, v[172:173]
	global_load_dwordx4 v[96:99], v[96:97], off
	s_nop 0
	global_load_dwordx4 v[100:103], v[100:101], off
	v_cndmask_b32_e64 v122, 0, 1, s[60:61]
	global_load_dwordx4 v[112:115], v[112:113], off
	v_pk_mul_f32 v[144:145], v[72:73], v[64:65]
	v_pk_mul_f32 v[120:121], v[8:9], v[4:5]
	v_cmp_ne_u32_e64 s[0:1], 1, v122
	v_mov_b32_e32 v243, 0
	s_and_saveexec_b64 s[84:85], s[4:5]
	s_cbranch_execz .LBB0_149
	v_pk_mul_f32 v[146:147], v[74:75], v[66:67]
	v_pk_mul_f32 v[122:123], v[10:11], v[6:7]
	s_and_b64 vcc, exec, s[0:1]
	ds_write_b128 v177, v[144:147]
	ds_write_b128 v178, v[120:123]
	s_cbranch_vccnz .LBB0_149
	s_ashr_i32 s83, s82, 31
	s_lshl_b64 s[14:15], s[82:83], 13
	v_lshl_add_u64 v[4:5], v[156:157], 0, s[14:15]
	v_lshl_add_u64 v[4:5], v[170:171], 2, v[4:5]
	v_mov_b32_e32 v244, v120
	v_mov_b32_e32 v245, v121
	v_mov_b32_e32 v246, v122
	v_mov_b32_e32 v247, v123
	v_mov_b32_e32 v248, v4
	v_mov_b32_e32 v249, v5
	v_mov_b32_e32 v243, 1

.LBB0_153:
	s_or_b64 exec, exec, s[84:85]
	v_mul_f32_e32 v5, 0xbfb8aa3b, v108
	v_exp_f32_e32 v5, v5
	v_mul_f32_e32 v72, 0xbfb8aa3b, v109
	v_exp_f32_e32 v72, v72
	v_mul_f32_e32 v9, v124, v108
	v_add_f32_e32 v5, 1.0, v5
	v_rcp_f32_e32 v5, v5
	v_add_f32_e32 v72, 1.0, v72
	v_mul_f32_e32 v108, 0xbfb8aa3b, v111
	v_rcp_f32_e32 v72, v72
	v_mul_f32_e32 v5, v9, v5
	v_mul_f32_e32 v9, 0xbfb8aa3b, v110
	v_exp_f32_e32 v9, v9
	v_exp_f32_e32 v108, v108
	v_mul_f32_e32 v73, v125, v109
	v_mul_f32_e32 v73, v73, v72
	v_add_f32_e32 v9, 1.0, v9
	v_rcp_f32_e32 v9, v9
	v_add_f32_e32 v72, 1.0, v108
	v_rcp_f32_e32 v72, v72
	v_mul_f32_e32 v108, v126, v110
	v_mul_f32_e32 v110, v108, v9
	v_mul_f32_e32 v9, v127, v111
	v_pk_mul_f32 v[104:105], v[116:117], v[104:105]
	v_mul_f32_e32 v111, v9, v72
	v_mov_b32_dpp v9, v128 row_ror:1 row_mask:0xf bank_mask:0xf
	v_mov_b32_dpp v116, v104 row_ror:1 row_mask:0xf bank_mask:0xf
	v_mov_b32_dpp v117, v104 row_ror:2 row_mask:0xf bank_mask:0xf
	v_mov_b32_dpp v108, v128 row_ror:2 row_mask:0xf bank_mask:0xf
	s_waitcnt vmcnt(3)
	v_cmp_eq_u32_e32 vcc, 1, v243
	s_and_saveexec_b64 s[84:85], vcc
	global_store_dwordx4 v[248:249], v[244:247], off sc1
	s_or_b64 exec, exec, s[84:85]
	v_cndmask_b32_e64 v115, v117, v108, s[8:9]
	v_cndmask_b32_e64 v113, v116, v9, s[6:7]
	v_mov_b32_e32 v108, v104
	v_mov_b32_e32 v109, v100
	v_pk_mul_f32 v[108:109], v[108:109], v[112:113]
	v_pk_mul_f32 v[106:107], v[118:119], v[106:107]
	v_fma_f32 v9, v96, v115, v109
	v_add_f32_e32 v9, v108, v9
	v_mul_f32_e32 v108, v5, v9
	v_mov_b32_dpp v109, v105 row_ror:1 row_mask:0xf bank_mask:0xf
	v_mov_b32_dpp v118, v105 row_ror:2 row_mask:0xf bank_mask:0xf
	v_mov_b32_dpp v5, v129 row_ror:1 row_mask:0xf bank_mask:0xf
	v_mov_b32_dpp v9, v129 row_ror:2 row_mask:0xf bank_mask:0xf
	v_cndmask_b32_e64 v113, v118, v9, s[8:9]
	v_cndmask_b32_e64 v9, v109, v5, s[6:7]
	v_mov_b32_e32 v104, v105
	v_mov_b32_e32 v105, v101
	v_pk_mul_f32 v[104:105], v[104:105], v[8:9]
	v_mov_b32_dpp v119, v106 row_ror:1 row_mask:0xf bank_mask:0xf
	v_fma_f32 v5, v97, v113, v105
	v_add_f32_e32 v5, v104, v5
	v_mul_f32_e32 v9, v73, v5
	v_mov_b32_dpp v122, v106 row_ror:2 row_mask:0xf bank_mask:0xf
	v_mov_b32_dpp v5, v130 row_ror:1 row_mask:0xf bank_mask:0xf
	v_mov_b32_dpp v73, v130 row_ror:2 row_mask:0xf bank_mask:0xf
	v_cndmask_b32_e64 v115, v119, v5, s[6:7]
	v_mov_b32_e32 v104, v106
	v_mov_b32_e32 v105, v102
	v_cndmask_b32_e64 v73, v122, v73, s[8:9]
	v_pk_mul_f32 v[104:105], v[104:105], v[114:115]
	v_mov_b32_dpp v123, v107 row_ror:2 row_mask:0xf bank_mask:0xf
	v_fma_f32 v5, v98, v73, v105
	v_add_f32_e32 v5, v104, v5
	v_mul_f32_e32 v73, v110, v5
	v_mov_b32_dpp v110, v107 row_ror:1 row_mask:0xf bank_mask:0xf
	v_mov_b32_dpp v5, v131 row_ror:1 row_mask:0xf bank_mask:0xf
	v_mov_b32_dpp v106, v131 row_ror:2 row_mask:0xf bank_mask:0xf
	v_cndmask_b32_e64 v5, v110, v5, s[6:7]
	v_mov_b32_e32 v104, v107
	v_mov_b32_e32 v105, v103
	v_pk_mul_f32 v[104:105], v[104:105], v[4:5]
	v_cndmask_b32_e64 v5, v123, v106, s[8:9]
	v_fma_f32 v5, v99, v5, v105
	v_add_f32_e32 v5, v104, v5
	v_mul_f32_e32 v5, v111, v5
	v_cvt_pk_bf16_f32 v104, v108, v9
	v_cvt_pk_bf16_f32 v105, v73, v5
	v_mul_f32_e32 v5, 0xbfb8aa3b, v84
	v_or_b32_e32 v72, 16, v64
	v_exp_f32_e32 v5, v5
	v_mul_f32_e32 v9, 0xbfb8aa3b, v85
	v_ashrrev_i32_e32 v73, 31, v72
	v_exp_f32_e32 v9, v9
	v_lshlrev_b64 v[72:73], 11, v[72:73]
	v_lshl_add_u64 v[72:73], s[28:29], 0, v[72:73]
	v_lshlrev_b64 v[106:107], 1, v[170:171]
	v_lshl_add_u64 v[72:73], v[72:73], 0, v[106:107]
	v_add_f32_e32 v5, 1.0, v5
	global_store_dwordx2 v[72:73], v[104:105], off
	v_rcp_f32_e32 v5, v5
	v_add_f32_e32 v9, 1.0, v9
	v_mul_f32_e32 v73, 0xbfb8aa3b, v86
	v_rcp_f32_e32 v9, v9
	v_exp_f32_e32 v73, v73
	v_mul_f32_e32 v72, v92, v84
	v_mul_f32_e32 v84, 0xbfb8aa3b, v87
	v_exp_f32_e32 v84, v84
	v_mul_f32_e32 v5, v72, v5
	v_mul_f32_e32 v72, v93, v85
	v_mul_f32_e32 v92, v72, v9
	v_add_f32_e32 v9, 1.0, v73
	v_rcp_f32_e32 v9, v9
	v_add_f32_e32 v72, 1.0, v84
	v_rcp_f32_e32 v72, v72
	v_mul_f32_e32 v73, v94, v86
	v_pk_mul_f32 v[80:81], v[88:89], v[80:81]
	v_mul_f32_e32 v73, v73, v9
	v_mul_f32_e32 v9, v95, v87
	v_mov_b32_dpp v87, v80 row_ror:1 row_mask:0xf bank_mask:0xf
	v_mov_b32_dpp v88, v80 row_ror:2 row_mask:0xf bank_mask:0xf
	v_cndmask_b32_e64 v113, v87, v116, s[6:7]
	v_mov_b32_e32 v84, v80
	v_mov_b32_e32 v85, v100
	v_mul_f32_e32 v86, v9, v72
	v_cndmask_b32_e64 v9, v88, v117, s[8:9]
	v_pk_mul_f32 v[84:85], v[84:85], v[112:113]
	v_mov_b32_dpp v89, v81 row_ror:2 row_mask:0xf bank_mask:0xf
	v_fma_f32 v9, v96, v9, v85
	v_add_f32_e32 v9, v84, v9
	v_mov_b32_dpp v85, v81 row_ror:1 row_mask:0xf bank_mask:0xf
	v_mul_f32_e32 v84, v5, v9
	v_cndmask_b32_e64 v9, v85, v109, s[6:7]
	v_mov_b32_e32 v80, v81
	v_mov_b32_e32 v81, v101
	v_pk_mul_f32 v[82:83], v[90:91], v[82:83]
	v_cndmask_b32_e64 v5, v89, v118, s[8:9]
	v_pk_mul_f32 v[80:81], v[80:81], v[8:9]
	v_mov_b32_dpp v90, v82 row_ror:1 row_mask:0xf bank_mask:0xf
	v_fma_f32 v5, v97, v5, v81
	v_add_f32_e32 v5, v80, v5
	v_mov_b32_dpp v91, v82 row_ror:2 row_mask:0xf bank_mask:0xf
	v_cndmask_b32_e64 v115, v90, v119, s[6:7]
	v_mov_b32_e32 v80, v82
	v_mov_b32_e32 v81, v102
	v_mul_f32_e32 v9, v92, v5
	v_cndmask_b32_e64 v5, v91, v122, s[8:9]
	v_pk_mul_f32 v[80:81], v[80:81], v[114:115]
	v_mov_b32_dpp v82, v83 row_ror:1 row_mask:0xf bank_mask:0xf
	v_fma_f32 v5, v98, v5, v81
	v_add_f32_e32 v5, v80, v5
	v_mul_f32_e32 v73, v73, v5
	v_mov_b32_dpp v92, v83 row_ror:2 row_mask:0xf bank_mask:0xf
	v_cndmask_b32_e64 v5, v82, v110, s[6:7]
	v_mov_b32_e32 v80, v83
	v_mov_b32_e32 v81, v103
	v_pk_mul_f32 v[80:81], v[80:81], v[4:5]
	v_cndmask_b32_e64 v5, v92, v123, s[8:9]
	v_fma_f32 v5, v99, v5, v81
	v_add_f32_e32 v5, v80, v5
	v_mul_f32_e32 v5, v86, v5
	v_cvt_pk_bf16_f32 v80, v84, v9
	v_cvt_pk_bf16_f32 v81, v73, v5
	v_mul_f32_e32 v5, 0xbfb8aa3b, v68
	v_exp_f32_e32 v5, v5
	v_mul_f32_e32 v9, 0xbfb8aa3b, v69
	v_or_b32_e32 v72, 32, v64
	v_exp_f32_e32 v9, v9
	v_add_f32_e32 v5, 1.0, v5
	v_rcp_f32_e32 v5, v5
	v_ashrrev_i32_e32 v73, 31, v72
	v_lshlrev_b64 v[72:73], 11, v[72:73]
	v_lshl_add_u64 v[72:73], s[28:29], 0, v[72:73]
	v_mul_f32_e32 v68, v76, v68
	v_lshl_add_u64 v[72:73], v[72:73], 0, v[106:107]
	v_mul_f32_e32 v5, v68, v5
	v_mul_f32_e32 v68, v77, v69
	v_add_f32_e32 v9, 1.0, v9
	v_mul_f32_e32 v69, 0xbfb8aa3b, v70
	global_store_dwordx2 v[72:73], v[80:81], off
	v_rcp_f32_e32 v9, v9
	v_exp_f32_e32 v69, v69
	v_mul_f32_e32 v72, 0xbfb8aa3b, v71
	v_exp_f32_e32 v72, v72
	v_mul_f32_e32 v73, v68, v9
	v_add_f32_e32 v9, 1.0, v69
	v_rcp_f32_e32 v9, v9
	v_add_f32_e32 v68, 1.0, v72
	v_rcp_f32_e32 v68, v68
	v_mul_f32_e32 v69, v78, v70
	v_mul_f32_e32 v69, v69, v9
	v_mul_f32_e32 v9, v79, v71
	v_mul_f32_e32 v72, v9, v68
	v_mov_b32_dpp v70, v144 row_ror:2 row_mask:0xf bank_mask:0xf
	v_mov_b32_dpp v9, v144 row_ror:1 row_mask:0xf bank_mask:0xf
	v_pk_mul_f32 v[66:67], v[74:75], v[66:67]
	v_cndmask_b32_e64 v74, v70, v88, s[8:9]
	v_cndmask_b32_e64 v113, v9, v87, s[6:7]
	v_mov_b32_e32 v70, v144
	v_mov_b32_e32 v71, v100
	v_pk_mul_f32 v[70:71], v[70:71], v[112:113]
	v_or_b32_e32 v68, 48, v64
	v_fma_f32 v9, v96, v74, v71
	v_add_f32_e32 v9, v70, v9
	v_mul_f32_e32 v74, v5, v9
	v_mov_b32_dpp v5, v145 row_ror:1 row_mask:0xf bank_mask:0xf
	v_mov_b32_dpp v9, v145 row_ror:2 row_mask:0xf bank_mask:0xf
	v_cndmask_b32_e64 v75, v9, v89, s[8:9]
	v_cndmask_b32_e64 v9, v5, v85, s[6:7]
	v_mov_b32_e32 v70, v145
	v_mov_b32_e32 v71, v101
	v_pk_mul_f32 v[70:71], v[70:71], v[8:9]
	v_pk_mul_f32 v[50:51], v[58:59], v[50:51]
	v_fma_f32 v5, v97, v75, v71
	v_add_f32_e32 v5, v70, v5
	v_mul_f32_e32 v9, v73, v5
	v_mov_b32_dpp v70, v66 row_ror:2 row_mask:0xf bank_mask:0xf
	v_mov_b32_dpp v5, v66 row_ror:1 row_mask:0xf bank_mask:0xf
	v_cndmask_b32_e64 v73, v70, v91, s[8:9]
	v_cndmask_b32_e64 v115, v5, v90, s[6:7]
	v_mov_b32_e32 v70, v66
	v_mov_b32_e32 v71, v102
	v_pk_mul_f32 v[70:71], v[70:71], v[114:115]
	v_mov_b32_e32 v66, v67
	v_fma_f32 v5, v98, v73, v71
	v_add_f32_e32 v5, v70, v5
	v_mul_f32_e32 v69, v69, v5
	v_mov_b32_dpp v70, v67 row_ror:2 row_mask:0xf bank_mask:0xf
	v_mov_b32_dpp v5, v67 row_ror:1 row_mask:0xf bank_mask:0xf
	v_cndmask_b32_e64 v5, v5, v82, s[6:7]
	v_mov_b32_e32 v67, v103
	v_pk_mul_f32 v[66:67], v[66:67], v[4:5]
	v_cndmask_b32_e64 v5, v70, v92, s[8:9]
	v_fma_f32 v5, v99, v5, v67
	v_add_f32_e32 v5, v66, v5
	v_mul_f32_e32 v5, v72, v5
	v_cvt_pk_bf16_f32 v66, v74, v9
	v_cvt_pk_bf16_f32 v67, v69, v5
	v_mul_f32_e32 v5, 0xbfb8aa3b, v52
	v_exp_f32_e32 v5, v5
	v_mul_f32_e32 v9, 0xbfb8aa3b, v53
	v_ashrrev_i32_e32 v69, 31, v68
	v_exp_f32_e32 v9, v9
	v_lshlrev_b64 v[68:69], 11, v[68:69]
	v_lshl_add_u64 v[68:69], s[28:29], 0, v[68:69]
	v_lshl_add_u64 v[68:69], v[68:69], 0, v[106:107]
	v_add_f32_e32 v5, 1.0, v5
	global_store_dwordx2 v[68:69], v[66:67], off
	v_rcp_f32_e32 v66, v5
	v_add_f32_e32 v5, 1.0, v9
	v_mul_f32_e32 v9, 0xbfb8aa3b, v54
	v_exp_f32_e32 v9, v9
	v_mul_f32_e32 v67, 0xbfb8aa3b, v55
	v_exp_f32_e32 v69, v67
	v_rcp_f32_e32 v67, v5
	v_add_f32_e32 v5, 1.0, v9
	v_rcp_f32_e32 v68, v5
	v_add_f32_e32 v5, 1.0, v69
	v_rcp_f32_e32 v69, v5
	v_pk_mul_f32 v[54:55], v[62:63], v[54:55]
	v_pk_mul_f32 v[52:53], v[60:61], v[52:53]
	v_pk_mul_f32 v[48:49], v[56:57], v[48:49]
	v_pk_mul_f32 v[52:53], v[52:53], v[66:67]
	v_pk_mul_f32 v[54:55], v[54:55], v[68:69]
	v_mov_b32_dpp v57, v48 row_ror:1 row_mask:0xf bank_mask:0xf
	v_mov_b32_dpp v56, v48 row_ror:2 row_mask:0xf bank_mask:0xf
	v_mov_b32_dpp v9, v49 row_ror:1 row_mask:0xf bank_mask:0xf
	v_mov_b32_dpp v58, v49 row_ror:2 row_mask:0xf bank_mask:0xf
	v_mov_b32_dpp v60, v50 row_ror:1 row_mask:0xf bank_mask:0xf
	v_mov_b32_dpp v59, v50 row_ror:2 row_mask:0xf bank_mask:0xf
	v_mov_b32_dpp v5, v51 row_ror:1 row_mask:0xf bank_mask:0xf
	v_mov_b32_dpp v61, v51 row_ror:2 row_mask:0xf bank_mask:0xf
	s_and_saveexec_b64 s[14:15], s[68:69]
	s_xor_b64 s[84:85], exec, s[14:15]
	s_cbranch_execz .LBB0_155
	ds_read_b128 v[66:69], v182
	ds_read_b128 v[70:73], v181
	v_mov_b32_e32 v62, v50
	v_mov_b32_e32 v63, v102
	s_waitcnt lgkmcnt(1)
	v_cndmask_b32_e64 v61, v61, v69, s[10:11]
	v_cndmask_b32_e64 v115, v60, v68, s[6:7]
	v_cndmask_b32_e64 v59, v59, v68, s[10:11]
	v_cndmask_b32_e64 v5, v5, v69, s[6:7]
	s_waitcnt lgkmcnt(0)
	v_cndmask_b32_e64 v69, v61, v73, s[6:7]
	v_pk_mul_f32 v[60:61], v[62:63], v[114:115]
	v_cndmask_b32_e64 v59, v59, v72, s[6:7]
	v_fma_f32 v59, v98, v59, v61
	v_add_f32_e32 v59, v60, v59
	v_cndmask_b32_e64 v9, v9, v67, s[6:7]
	v_mov_b32_e32 v60, v49
	v_mov_b32_e32 v61, v101
	v_pk_mul_f32 v[60:61], v[60:61], v[8:9]
	v_cndmask_b32_e64 v9, v58, v67, s[10:11]
	v_cndmask_b32_e64 v9, v9, v71, s[6:7]
	v_fma_f32 v9, v97, v9, v61
	v_add_f32_e32 v9, v60, v9
	v_mul_f32_e32 v54, v54, v59
	v_mul_f32_e32 v9, v53, v9
	v_cndmask_b32_e64 v113, v57, v66, s[6:7]
	v_mov_b32_e32 v58, v48
	v_mov_b32_e32 v59, v100
	v_cndmask_b32_e64 v53, v56, v66, s[10:11]
	v_pk_mul_f32 v[58:59], v[58:59], v[112:113]
	v_cndmask_b32_e64 v53, v53, v70, s[6:7]
	v_fma_f32 v53, v96, v53, v59
	v_add_f32_e32 v53, v58, v53
	v_mul_f32_e32 v56, v52, v53
	v_mov_b32_e32 v52, v51
	v_mov_b32_e32 v53, v103
	v_pk_mul_f32 v[52:53], v[52:53], v[4:5]
	s_nop 0
	v_fma_f32 v5, v99, v69, v53
	v_add_f32_e32 v5, v52, v5
	v_mul_f32_e32 v5, v55, v5
	v_cvt_pk_bf16_f32 v52, v56, v9
	v_cvt_pk_bf16_f32 v53, v54, v5
	v_lshlrev_b64 v[54:55], 11, v[64:65]
	v_lshl_add_u64 v[54:55], s[28:29], 0, v[54:55]
	v_lshl_add_u64 v[54:55], v[170:171], 1, v[54:55]
	v_add_co_u32_e32 v54, vcc, 0x40000, v54
	s_nop 1
	v_addc_co_u32_e32 v55, vcc, 0, v55, vcc
	global_store_dwordx2 v[54:55], v[52:53], off

	.amdhsa_kernel _Z14fwd_megakernel4Args
		.amdhsa_group_segment_fixed_size 0
		.amdhsa_private_segment_fixed_size 0
		.amdhsa_kernarg_size 368
		.amdhsa_user_sgpr_count 2
		.amdhsa_user_sgpr_dispatch_ptr 0
		.amdhsa_user_sgpr_queue_ptr 0
		.amdhsa_user_sgpr_kernarg_segment_ptr 1
		.amdhsa_user_sgpr_dispatch_id 0
		.amdhsa_user_sgpr_kernarg_preload_length 0
		.amdhsa_user_sgpr_kernarg_preload_offset 0
		.amdhsa_user_sgpr_private_segment_size 0
		.amdhsa_uses_dynamic_stack 0
		.amdhsa_enable_private_segment 0
		.amdhsa_system_sgpr_workgroup_id_x 1
		.amdhsa_system_sgpr_workgroup_id_y 0
		.amdhsa_system_sgpr_workgroup_id_z 0
		.amdhsa_system_sgpr_workgroup_info 0
		.amdhsa_system_vgpr_workitem_id 2
		.amdhsa_next_free_vgpr 250
		.amdhsa_next_free_sgpr 100
		.amdhsa_accum_offset 252
		.amdhsa_reserve_vcc 1
		.amdhsa_float_round_mode_32 0
		.amdhsa_float_round_mode_16_64 0
		.amdhsa_float_denorm_mode_32 3
		.amdhsa_float_denorm_mode_16_64 3
		.amdhsa_dx10_clamp 1
		.amdhsa_ieee_mode 1
		.amdhsa_fp16_overflow 0
		.amdhsa_tg_split 0
		.amdhsa_exception_fp_ieee_invalid_op 0
		.amdhsa_exception_fp_denorm_src 0
		.amdhsa_exception_fp_ieee_div_zero 0
		.amdhsa_exception_fp_ieee_overflow 0
		.amdhsa_exception_fp_ieee_underflow 0
		.amdhsa_exception_fp_ieee_inexact 0
		.amdhsa_exception_int_div_zero 0
	.end_amdhsa_kernel

amdhsa.kernels:
  - .agpr_count:     0
    .args:
      - .offset:         0
        .size:           112
        .value_kind:     by_value
      - .offset:         112
        .size:           4
        .value_kind:     hidden_block_count_x
      - .offset:         116
        .size:           4
        .value_kind:     hidden_block_count_y
      - .offset:         120
        .size:           4
        .value_kind:     hidden_block_count_z
      - .offset:         124
        .size:           2
        .value_kind:     hidden_group_size_x
      - .offset:         126
        .size:           2
        .value_kind:     hidden_group_size_y
      - .offset:         128
        .size:           2
        .value_kind:     hidden_group_size_z
      - .offset:         130
        .size:           2
        .value_kind:     hidden_remainder_x
      - .offset:         132
        .size:           2
        .value_kind:     hidden_remainder_y
      - .offset:         134
        .size:           2
        .value_kind:     hidden_remainder_z
      - .offset:         152
        .size:           8
        .value_kind:     hidden_global_offset_x
      - .offset:         160
        .size:           8
        .value_kind:     hidden_global_offset_y
      - .offset:         168
        .size:           8
        .value_kind:     hidden_global_offset_z
      - .offset:         176
        .size:           2
        .value_kind:     hidden_grid_dims
      - .offset:         200
        .size:           8
        .value_kind:     hidden_multigrid_sync_arg
      - .offset:         232
        .size:           4
        .value_kind:     hidden_dynamic_lds_size
    .group_segment_fixed_size: 0
    .kernarg_segment_align: 8
    .kernarg_segment_size: 368
    .language:       OpenCL C
    .language_version:
      - 2
      - 0
    .max_flat_workgroup_size: 512
    .name:           _Z14fwd_megakernel4Args
    .private_segment_fixed_size: 0
    .sgpr_count:     106
    .sgpr_spill_count: 10
    .symbol:         _Z14fwd_megakernel4Args.kd
    .uniform_work_group_size: 1
    .uses_dynamic_stack: false
    .vgpr_count:     250
    .vgpr_spill_count: 0
    .wavefront_size: 64
